# early decode units on workgroups 192..255 only (64 units)
# baseline (speedup 1.0000x reference)
; #define LAS __attribute__((address_space(3)))
; __device__ __forceinline__ int fresh_lane() { int l; asm volatile("v_mbcnt_lo_u32_b32 %0, -1, 0\n\tv_mbcnt_hi_u32_b32 %0, -1, %0" : "=v"(l)); return l; }
; __device__ __forceinline__ unsigned xb_xcc_id() { return (unsigned)__builtin_amdgcn_s_getreg((3 << 11) | 20) & 0xFu; }
; __device__ __forceinline__ void phase_attention(const Params& P, const Ctx& C, int parts, int qset) {
;     unsigned* qc = (unsigned*)(P.ws + WS_CTL) + CW_QUEUE + qset * 512;
;     volatile LAS unsigned* slot = (volatile LAS unsigned*)(C.lds + MISC_OFF) + 16;
;     const bool fixed_ok = ((const float*)(P.ws + WS_PEB))[768] < 100.f;
;     const int x0 = (int)(xb_xcc_id() & 7u);
;     for (int i = 0; i < 8; ++i) { const int x = (x0 + i) & 7;
;         for (;;) {
;             __syncthreads();
;             if (C.wave == 0 && fresh_lane() == 0) *slot = __hip_atomic_fetch_add(qc + 64 * x, 1u, __ATOMIC_RELAXED, __HIP_MEMORY_SCOPE_AGENT);
;             __syncthreads();
;             const unsigned u = *slot;
;             if (u >= 128u) break;
;             const int us = __builtin_amdgcn_readfirstlane((int)u);
;             int pq = -1, dq = -1;
;             if (us < 96) { const int k = us / 3, r = us - 3 * k; if (r == 0) pq = 63 - k; else dq = 2 * k + r - 1; } else pq = 127 - us;
;             if (pq >= 0) { if (parts & 1) { if (fixed_ok) attn_prompt_unit<true>(P, C, x, pq); else attn_prompt_unit<false>(P, C, x, pq); } }
;             else { if (parts & 2) attn_decode_unit(P, C, x * 64 + dq); }
.LBB0_1136:
	s_bitcmp1_b32 s101, 1
	s_cbranch_scc1 .Lmy_e7
	s_bitset1_b32 s101, 1
	s_cmpk_lg_i32 s68, 0x100
	s_cbranch_scc1 .Lmy_e7
	s_bitset1_b32 s101, 3
	v_readlane_b32 s99, v254, 10
	s_cmpk_lt_u32 s99, 192
	s_cbranch_scc1 .Lmy_e7
	s_and_b32 s100, s99, 31
	s_mul_i32 s100, s100, 3
	s_add_i32 s100, s100, 1
	s_bitset1_b32 s101, 0
	s_waitcnt vmcnt(0)
	s_barrier
	s_mov_b64 s[2:3], -1
	s_branch .LBB0_1192

; __device__ __forceinline__ void phase_attention(const Params& P, const Ctx& C, int parts, int qset) {
;     ...
;             const unsigned u = *slot;
;             if (u >= 128u) break;
;             const int us = __builtin_amdgcn_readfirstlane((int)u);
;             int pq = -1, dq = -1;
;             if (us < 96) { const int k = us / 3, r = us - 3 * k; if (r == 0) pq = 63 - k; else dq = 2 * k + r - 1; } else pq = 127 - us;
;             if (pq >= 0) { if (parts & 1) { if (fixed_ok) attn_prompt_unit<true>(P, C, x, pq); else attn_prompt_unit<false>(P, C, x, pq); } }
;             else { if (parts & 2) attn_decode_unit(P, C, x * 64 + dq); }
.LBB0_1215:
	s_bitcmp1_b32 s101, 0
	s_cbranch_scc1 .Lmy_e8
	s_bitcmp1_b32 s101, 3
	s_cbranch_scc0 .Lmy_e8
	v_readlane_b32 s99, v254, 13
	s_add_i32 s99, s99, s4
	s_cmpk_lt_u32 s99, 384
	s_cbranch_scc1 .Lmy_e8
	s_bitcmp0_b32 s4, 0
	s_cbranch_scc1 .LBB0_1200
